# in-proj gate / GLU outputs (read two phases later) stored non-temporal so the scan operands stay in the Infinity Cache
# speedup vs baseline: 1.0186x; 1.0014x over previous
; __device__ __forceinline__ unsigned cvt_pk_bf16(float lo, float hi) { unsigned r; asm volatile("v_cvt_pk_bf16_f32 %0, %1, %2" : "=v"(r) : "v"(lo), "v"(hi)); return r; }
; __device__ __forceinline__ float siluf_(float v) { return v * __builtin_amdgcn_rcpf(1.f + __expf(-v)); }
;     __device__ __forceinline__ void operator()(const f32x4 (&acc)[2][2][4][2], const pg8::Unit& u, int wr, int wc, int fr, int fq) const {
;     ...
;             bf16_t* D = (bf16_t*)(ws + (pn < 10 ? WS_GA : WS_GB));
;             const int colb = 256 * (pn < 10 ? pn - 8 : pn - 14) + 32 * wc + 8 * fq;
; #pragma unroll
;             for (int ai = 0; ai < 2; ++ai)
; #pragma unroll
;                 for (int m = 0; m < 4; ++m) {
;                     const size_t row = (size_t)(row0 + ai * 128 + m * 16);
; #pragma unroll
;                     for (int bj = 0; bj < 2; ++bj) {
;                         f32x4 v0 = acc[ai][bj][m][0], v1 = acc[ai][bj][m][1];
; #pragma unroll
;                         for (int j = 0; j < 4; ++j) { v0[j] = siluf_(v0[j]); v1[j] = siluf_(v1[j]); }
;                         u32x4 o = {cvt_pk_bf16(v0[0], v0[1]), cvt_pk_bf16(v0[2], v0[3]), cvt_pk_bf16(v1[0], v1[1]), cvt_pk_bf16(v1[2], v1[3])};
;                         *(u32x4*)(D + row * 512 + colb + 128 * bj) = o;
;                     }
.Lgate_new:
	s_mov_b32 s4, 0xfb00000
	s_cmp_lt_u32 s10, 10
	s_cselect_b32 s4, s4, 0x13b00000
	s_cselect_b32 s5, -8, -14
	s_add_u32 s14, s70, s4
	s_addc_u32 s15, s71, 0
	s_add_i32 s4, s5, s10
	v_lshl_or_b32 v173, s4, 8, v183
	v_lshlrev_b32_e32 v173, 1, v173
	v_lshl_add_u32 v173, v172, 10, v173
	v_mov_b32_e32 v130, 0xbfb8aa3b
	v_mov_b32_e32 v131, 0xbfb8aa3b
	s_add_u32 s4, s14, 0
	s_addc_u32 s5, s15, 0
	v_pk_mul_f32 v[132:133], v[94:95], v[130:131]
	v_pk_mul_f32 v[134:135], v[96:97], v[130:131]
	v_pk_mul_f32 v[136:137], v[126:127], v[130:131]
	v_pk_mul_f32 v[138:139], v[128:129], v[130:131]
	v_exp_f32_e32 v132, v132
	v_exp_f32_e32 v133, v133
	v_exp_f32_e32 v134, v134
	v_exp_f32_e32 v135, v135
	v_exp_f32_e32 v136, v136
	v_exp_f32_e32 v137, v137
	v_exp_f32_e32 v138, v138
	v_exp_f32_e32 v139, v139
	v_pk_add_f32 v[132:133], v[132:133], 1.0 op_sel_hi:[1,0]
	v_pk_add_f32 v[134:135], v[134:135], 1.0 op_sel_hi:[1,0]
	v_pk_add_f32 v[136:137], v[136:137], 1.0 op_sel_hi:[1,0]
	v_pk_add_f32 v[138:139], v[138:139], 1.0 op_sel_hi:[1,0]
	v_rcp_f32_e32 v132, v132
	v_rcp_f32_e32 v133, v133
	v_rcp_f32_e32 v134, v134
	v_rcp_f32_e32 v135, v135
	v_rcp_f32_e32 v136, v136
	v_rcp_f32_e32 v137, v137
	v_rcp_f32_e32 v138, v138
	v_rcp_f32_e32 v139, v139
	v_pk_mul_f32 v[132:133], v[94:95], v[132:133]
	v_pk_mul_f32 v[134:135], v[96:97], v[134:135]
	v_pk_mul_f32 v[136:137], v[126:127], v[136:137]
	v_pk_mul_f32 v[138:139], v[128:129], v[138:139]
	v_cvt_pk_bf16_f32 v140, v132, v133
	v_cvt_pk_bf16_f32 v141, v134, v135
	v_cvt_pk_bf16_f32 v142, v136, v137
	v_cvt_pk_bf16_f32 v143, v138, v139
	global_store_dwordx4 v173, v[140:143], s[4:5] offset:0 nt
	v_pk_mul_f32 v[132:133], v[122:123], v[130:131]
	v_pk_mul_f32 v[134:135], v[124:125], v[130:131]
	v_pk_mul_f32 v[136:137], v[78:79], v[130:131]
	v_pk_mul_f32 v[138:139], v[80:81], v[130:131]
	v_exp_f32_e32 v132, v132
	v_exp_f32_e32 v133, v133
	v_exp_f32_e32 v134, v134
	v_exp_f32_e32 v135, v135
	v_exp_f32_e32 v136, v136
	v_exp_f32_e32 v137, v137
	v_exp_f32_e32 v138, v138
	v_exp_f32_e32 v139, v139
	v_pk_add_f32 v[132:133], v[132:133], 1.0 op_sel_hi:[1,0]
	v_pk_add_f32 v[134:135], v[134:135], 1.0 op_sel_hi:[1,0]
	v_pk_add_f32 v[136:137], v[136:137], 1.0 op_sel_hi:[1,0]
	v_pk_add_f32 v[138:139], v[138:139], 1.0 op_sel_hi:[1,0]
	v_rcp_f32_e32 v132, v132
	v_rcp_f32_e32 v133, v133
	v_rcp_f32_e32 v134, v134
	v_rcp_f32_e32 v135, v135
	v_rcp_f32_e32 v136, v136
	v_rcp_f32_e32 v137, v137
	v_rcp_f32_e32 v138, v138
	v_rcp_f32_e32 v139, v139
	v_pk_mul_f32 v[132:133], v[122:123], v[132:133]
	v_pk_mul_f32 v[134:135], v[124:125], v[134:135]
	v_pk_mul_f32 v[136:137], v[78:79], v[136:137]
	v_pk_mul_f32 v[138:139], v[80:81], v[138:139]
	v_cvt_pk_bf16_f32 v144, v132, v133
	v_cvt_pk_bf16_f32 v145, v134, v135
	v_cvt_pk_bf16_f32 v146, v136, v137
	v_cvt_pk_bf16_f32 v147, v138, v139
	global_store_dwordx4 v173, v[144:147], s[4:5] offset:256 nt
	s_add_u32 s4, s14, 16384
	s_addc_u32 s5, s15, 0
	v_pk_mul_f32 v[132:133], v[90:91], v[130:131]
	v_pk_mul_f32 v[134:135], v[92:93], v[130:131]
	v_pk_mul_f32 v[136:137], v[118:119], v[130:131]
	v_pk_mul_f32 v[138:139], v[120:121], v[130:131]
	v_exp_f32_e32 v132, v132
	v_exp_f32_e32 v133, v133
	v_exp_f32_e32 v134, v134
	v_exp_f32_e32 v135, v135
	v_exp_f32_e32 v136, v136
	v_exp_f32_e32 v137, v137
	v_exp_f32_e32 v138, v138
	v_exp_f32_e32 v139, v139
	v_pk_add_f32 v[132:133], v[132:133], 1.0 op_sel_hi:[1,0]
	v_pk_add_f32 v[134:135], v[134:135], 1.0 op_sel_hi:[1,0]
	v_pk_add_f32 v[136:137], v[136:137], 1.0 op_sel_hi:[1,0]
	v_pk_add_f32 v[138:139], v[138:139], 1.0 op_sel_hi:[1,0]
	v_rcp_f32_e32 v132, v132
	v_rcp_f32_e32 v133, v133
	v_rcp_f32_e32 v134, v134
	v_rcp_f32_e32 v135, v135
	v_rcp_f32_e32 v136, v136
	v_rcp_f32_e32 v137, v137
	v_rcp_f32_e32 v138, v138
	v_rcp_f32_e32 v139, v139
	v_pk_mul_f32 v[132:133], v[90:91], v[132:133]
	v_pk_mul_f32 v[134:135], v[92:93], v[134:135]
	v_pk_mul_f32 v[136:137], v[118:119], v[136:137]
	v_pk_mul_f32 v[138:139], v[120:121], v[138:139]
	v_cvt_pk_bf16_f32 v140, v132, v133
	v_cvt_pk_bf16_f32 v141, v134, v135
	v_cvt_pk_bf16_f32 v142, v136, v137
	v_cvt_pk_bf16_f32 v143, v138, v139
	global_store_dwordx4 v173, v[140:143], s[4:5] offset:0 nt
	v_pk_mul_f32 v[132:133], v[114:115], v[130:131]
	v_pk_mul_f32 v[134:135], v[116:117], v[130:131]
	v_pk_mul_f32 v[136:137], v[74:75], v[130:131]
	v_pk_mul_f32 v[138:139], v[76:77], v[130:131]
	v_exp_f32_e32 v132, v132
	v_exp_f32_e32 v133, v133
	v_exp_f32_e32 v134, v134
	v_exp_f32_e32 v135, v135
	v_exp_f32_e32 v136, v136
	v_exp_f32_e32 v137, v137
	v_exp_f32_e32 v138, v138
	v_exp_f32_e32 v139, v139
	v_pk_add_f32 v[132:133], v[132:133], 1.0 op_sel_hi:[1,0]
	v_pk_add_f32 v[134:135], v[134:135], 1.0 op_sel_hi:[1,0]
	v_pk_add_f32 v[136:137], v[136:137], 1.0 op_sel_hi:[1,0]
	v_pk_add_f32 v[138:139], v[138:139], 1.0 op_sel_hi:[1,0]
	v_rcp_f32_e32 v132, v132
	v_rcp_f32_e32 v133, v133
	v_rcp_f32_e32 v134, v134
	v_rcp_f32_e32 v135, v135
	v_rcp_f32_e32 v136, v136
	v_rcp_f32_e32 v137, v137
	v_rcp_f32_e32 v138, v138
	v_rcp_f32_e32 v139, v139
	v_pk_mul_f32 v[132:133], v[114:115], v[132:133]
	v_pk_mul_f32 v[134:135], v[116:117], v[134:135]
	v_pk_mul_f32 v[136:137], v[74:75], v[136:137]
	v_pk_mul_f32 v[138:139], v[76:77], v[138:139]
	v_cvt_pk_bf16_f32 v144, v132, v133
	v_cvt_pk_bf16_f32 v145, v134, v135
	v_cvt_pk_bf16_f32 v146, v136, v137
	v_cvt_pk_bf16_f32 v147, v138, v139
	global_store_dwordx4 v173, v[144:147], s[4:5] offset:256 nt
	s_add_u32 s4, s14, 32768
	s_addc_u32 s5, s15, 0
	v_pk_mul_f32 v[132:133], v[86:87], v[130:131]
	v_pk_mul_f32 v[134:135], v[88:89], v[130:131]
	v_pk_mul_f32 v[136:137], v[110:111], v[130:131]
	v_pk_mul_f32 v[138:139], v[112:113], v[130:131]
; __device__ __forceinline__ unsigned cvt_pk_bf16(float lo, float hi) { unsigned r; asm volatile("v_cvt_pk_bf16_f32 %0, %1, %2" : "=v"(r) : "v"(lo), "v"(hi)); return r; }
; __device__ __forceinline__ float siluf_(float v) { return v * __builtin_amdgcn_rcpf(1.f + __expf(-v)); }
;     __device__ __forceinline__ void operator()(const f32x4 (&acc)[2][2][4][2], const pg8::Unit& u, int wr, int wc, int fr, int fq) const {
;     ...
;             bf16_t* D = (bf16_t*)(ws + (pn < 10 ? WS_GA : WS_GB));
;             const int colb = 256 * (pn < 10 ? pn - 8 : pn - 14) + 32 * wc + 8 * fq;
; #pragma unroll
;             for (int ai = 0; ai < 2; ++ai)
; #pragma unroll
;                 for (int m = 0; m < 4; ++m) {
;                     const size_t row = (size_t)(row0 + ai * 128 + m * 16);
; #pragma unroll
;                     for (int bj = 0; bj < 2; ++bj) {
;                         f32x4 v0 = acc[ai][bj][m][0], v1 = acc[ai][bj][m][1];
; #pragma unroll
;                         for (int j = 0; j < 4; ++j) { v0[j] = siluf_(v0[j]); v1[j] = siluf_(v1[j]); }
;                         u32x4 o = {cvt_pk_bf16(v0[0], v0[1]), cvt_pk_bf16(v0[2], v0[3]), cvt_pk_bf16(v1[0], v1[1]), cvt_pk_bf16(v1[2], v1[3])};
;                         *(u32x4*)(D + row * 512 + colb + 128 * bj) = o;
;                     }
	v_exp_f32_e32 v132, v132
	v_exp_f32_e32 v133, v133
	v_exp_f32_e32 v134, v134
	v_exp_f32_e32 v135, v135
	v_exp_f32_e32 v136, v136
	v_exp_f32_e32 v137, v137
	v_exp_f32_e32 v138, v138
	v_exp_f32_e32 v139, v139
	v_pk_add_f32 v[132:133], v[132:133], 1.0 op_sel_hi:[1,0]
	v_pk_add_f32 v[134:135], v[134:135], 1.0 op_sel_hi:[1,0]
	v_pk_add_f32 v[136:137], v[136:137], 1.0 op_sel_hi:[1,0]
	v_pk_add_f32 v[138:139], v[138:139], 1.0 op_sel_hi:[1,0]
	v_rcp_f32_e32 v132, v132
	v_rcp_f32_e32 v133, v133
	v_rcp_f32_e32 v134, v134
	v_rcp_f32_e32 v135, v135
	v_rcp_f32_e32 v136, v136
	v_rcp_f32_e32 v137, v137
	v_rcp_f32_e32 v138, v138
	v_rcp_f32_e32 v139, v139
	v_pk_mul_f32 v[132:133], v[86:87], v[132:133]
	v_pk_mul_f32 v[134:135], v[88:89], v[134:135]
	v_pk_mul_f32 v[136:137], v[110:111], v[136:137]
	v_pk_mul_f32 v[138:139], v[112:113], v[138:139]
	v_cvt_pk_bf16_f32 v140, v132, v133
	v_cvt_pk_bf16_f32 v141, v134, v135
	v_cvt_pk_bf16_f32 v142, v136, v137
	v_cvt_pk_bf16_f32 v143, v138, v139
	global_store_dwordx4 v173, v[140:143], s[4:5] offset:0 nt
	v_pk_mul_f32 v[132:133], v[106:107], v[130:131]
	v_pk_mul_f32 v[134:135], v[108:109], v[130:131]
	v_pk_mul_f32 v[136:137], v[70:71], v[130:131]
	v_pk_mul_f32 v[138:139], v[72:73], v[130:131]
	v_exp_f32_e32 v132, v132
	v_exp_f32_e32 v133, v133
	v_exp_f32_e32 v134, v134
	v_exp_f32_e32 v135, v135
	v_exp_f32_e32 v136, v136
	v_exp_f32_e32 v137, v137
	v_exp_f32_e32 v138, v138
	v_exp_f32_e32 v139, v139
	v_pk_add_f32 v[132:133], v[132:133], 1.0 op_sel_hi:[1,0]
	v_pk_add_f32 v[134:135], v[134:135], 1.0 op_sel_hi:[1,0]
	v_pk_add_f32 v[136:137], v[136:137], 1.0 op_sel_hi:[1,0]
	v_pk_add_f32 v[138:139], v[138:139], 1.0 op_sel_hi:[1,0]
	v_rcp_f32_e32 v132, v132
	v_rcp_f32_e32 v133, v133
	v_rcp_f32_e32 v134, v134
	v_rcp_f32_e32 v135, v135
	v_rcp_f32_e32 v136, v136
	v_rcp_f32_e32 v137, v137
	v_rcp_f32_e32 v138, v138
	v_rcp_f32_e32 v139, v139
	v_pk_mul_f32 v[132:133], v[106:107], v[132:133]
	v_pk_mul_f32 v[134:135], v[108:109], v[134:135]
	v_pk_mul_f32 v[136:137], v[70:71], v[136:137]
	v_pk_mul_f32 v[138:139], v[72:73], v[138:139]
	v_cvt_pk_bf16_f32 v144, v132, v133
	v_cvt_pk_bf16_f32 v145, v134, v135
	v_cvt_pk_bf16_f32 v146, v136, v137
	v_cvt_pk_bf16_f32 v147, v138, v139
	global_store_dwordx4 v173, v[144:147], s[4:5] offset:256 nt
	s_add_u32 s4, s14, 49152
	s_addc_u32 s5, s15, 0
	v_pk_mul_f32 v[132:133], v[82:83], v[130:131]
	v_pk_mul_f32 v[134:135], v[84:85], v[130:131]
	v_pk_mul_f32 v[136:137], v[102:103], v[130:131]
	v_pk_mul_f32 v[138:139], v[104:105], v[130:131]
	v_exp_f32_e32 v132, v132
	v_exp_f32_e32 v133, v133
	v_exp_f32_e32 v134, v134
	v_exp_f32_e32 v135, v135
	v_exp_f32_e32 v136, v136
	v_exp_f32_e32 v137, v137
	v_exp_f32_e32 v138, v138
	v_exp_f32_e32 v139, v139
	v_pk_add_f32 v[132:133], v[132:133], 1.0 op_sel_hi:[1,0]
	v_pk_add_f32 v[134:135], v[134:135], 1.0 op_sel_hi:[1,0]
	v_pk_add_f32 v[136:137], v[136:137], 1.0 op_sel_hi:[1,0]
	v_pk_add_f32 v[138:139], v[138:139], 1.0 op_sel_hi:[1,0]
	v_rcp_f32_e32 v132, v132
	v_rcp_f32_e32 v133, v133
	v_rcp_f32_e32 v134, v134
	v_rcp_f32_e32 v135, v135
	v_rcp_f32_e32 v136, v136
	v_rcp_f32_e32 v137, v137
	v_rcp_f32_e32 v138, v138
	v_rcp_f32_e32 v139, v139
	v_pk_mul_f32 v[132:133], v[82:83], v[132:133]
	v_pk_mul_f32 v[134:135], v[84:85], v[134:135]
	v_pk_mul_f32 v[136:137], v[102:103], v[136:137]
	v_pk_mul_f32 v[138:139], v[104:105], v[138:139]
	v_cvt_pk_bf16_f32 v140, v132, v133
	v_cvt_pk_bf16_f32 v141, v134, v135
	v_cvt_pk_bf16_f32 v142, v136, v137
	v_cvt_pk_bf16_f32 v143, v138, v139
	global_store_dwordx4 v173, v[140:143], s[4:5] offset:0 nt
	v_pk_mul_f32 v[132:133], v[98:99], v[130:131]
	v_pk_mul_f32 v[134:135], v[100:101], v[130:131]
	v_pk_mul_f32 v[136:137], v[66:67], v[130:131]
	v_pk_mul_f32 v[138:139], v[68:69], v[130:131]
	v_exp_f32_e32 v132, v132
	v_exp_f32_e32 v133, v133
	v_exp_f32_e32 v134, v134
	v_exp_f32_e32 v135, v135
	v_exp_f32_e32 v136, v136
	v_exp_f32_e32 v137, v137
	v_exp_f32_e32 v138, v138
	v_exp_f32_e32 v139, v139
	v_pk_add_f32 v[132:133], v[132:133], 1.0 op_sel_hi:[1,0]
	v_pk_add_f32 v[134:135], v[134:135], 1.0 op_sel_hi:[1,0]
	v_pk_add_f32 v[136:137], v[136:137], 1.0 op_sel_hi:[1,0]
	v_pk_add_f32 v[138:139], v[138:139], 1.0 op_sel_hi:[1,0]
	v_rcp_f32_e32 v132, v132
	v_rcp_f32_e32 v133, v133
	v_rcp_f32_e32 v134, v134
	v_rcp_f32_e32 v135, v135
	v_rcp_f32_e32 v136, v136
	v_rcp_f32_e32 v137, v137
	v_rcp_f32_e32 v138, v138
	v_rcp_f32_e32 v139, v139
	v_pk_mul_f32 v[132:133], v[98:99], v[132:133]
	v_pk_mul_f32 v[134:135], v[100:101], v[134:135]
	v_pk_mul_f32 v[136:137], v[66:67], v[136:137]
	v_pk_mul_f32 v[138:139], v[68:69], v[138:139]
	v_cvt_pk_bf16_f32 v144, v132, v133
	v_cvt_pk_bf16_f32 v145, v134, v135
	v_cvt_pk_bf16_f32 v146, v136, v137
	v_cvt_pk_bf16_f32 v147, v138, v139
	global_store_dwordx4 v173, v[144:147], s[4:5] offset:256 nt
	s_add_u32 s4, s14, 131072
	s_addc_u32 s5, s15, 0
	v_pk_mul_f32 v[132:133], v[30:31], v[130:131]
	v_pk_mul_f32 v[134:135], v[32:33], v[130:131]
	v_pk_mul_f32 v[136:137], v[62:63], v[130:131]
	v_pk_mul_f32 v[138:139], v[64:65], v[130:131]
	v_exp_f32_e32 v132, v132
	v_exp_f32_e32 v133, v133
	v_exp_f32_e32 v134, v134
	v_exp_f32_e32 v135, v135
	v_exp_f32_e32 v136, v136
	v_exp_f32_e32 v137, v137
	v_exp_f32_e32 v138, v138
	v_exp_f32_e32 v139, v139
	v_pk_add_f32 v[132:133], v[132:133], 1.0 op_sel_hi:[1,0]
	v_pk_add_f32 v[134:135], v[134:135], 1.0 op_sel_hi:[1,0]
	v_pk_add_f32 v[136:137], v[136:137], 1.0 op_sel_hi:[1,0]
	v_pk_add_f32 v[138:139], v[138:139], 1.0 op_sel_hi:[1,0]
	v_rcp_f32_e32 v132, v132
	v_rcp_f32_e32 v133, v133
	v_rcp_f32_e32 v134, v134
	v_rcp_f32_e32 v135, v135
	v_rcp_f32_e32 v136, v136
	v_rcp_f32_e32 v137, v137
; __device__ __forceinline__ unsigned cvt_pk_bf16(float lo, float hi) { unsigned r; asm volatile("v_cvt_pk_bf16_f32 %0, %1, %2" : "=v"(r) : "v"(lo), "v"(hi)); return r; }
; __device__ __forceinline__ float siluf_(float v) { return v * __builtin_amdgcn_rcpf(1.f + __expf(-v)); }
;     __device__ __forceinline__ void operator()(const f32x4 (&acc)[2][2][4][2], const pg8::Unit& u, int wr, int wc, int fr, int fq) const {
;     ...
;             bf16_t* D = (bf16_t*)(ws + (pn < 10 ? WS_GA : WS_GB));
;             const int colb = 256 * (pn < 10 ? pn - 8 : pn - 14) + 32 * wc + 8 * fq;
; #pragma unroll
;             for (int ai = 0; ai < 2; ++ai)
; #pragma unroll
;                 for (int m = 0; m < 4; ++m) {
;                     const size_t row = (size_t)(row0 + ai * 128 + m * 16);
; #pragma unroll
;                     for (int bj = 0; bj < 2; ++bj) {
;                         f32x4 v0 = acc[ai][bj][m][0], v1 = acc[ai][bj][m][1];
; #pragma unroll
;                         for (int j = 0; j < 4; ++j) { v0[j] = siluf_(v0[j]); v1[j] = siluf_(v1[j]); }
;                         u32x4 o = {cvt_pk_bf16(v0[0], v0[1]), cvt_pk_bf16(v0[2], v0[3]), cvt_pk_bf16(v1[0], v1[1]), cvt_pk_bf16(v1[2], v1[3])};
;                         *(u32x4*)(D + row * 512 + colb + 128 * bj) = o;
;                     }
	v_rcp_f32_e32 v138, v138
	v_rcp_f32_e32 v139, v139
	v_pk_mul_f32 v[132:133], v[30:31], v[132:133]
	v_pk_mul_f32 v[134:135], v[32:33], v[134:135]
	v_pk_mul_f32 v[136:137], v[62:63], v[136:137]
	v_pk_mul_f32 v[138:139], v[64:65], v[138:139]
	v_cvt_pk_bf16_f32 v140, v132, v133
	v_cvt_pk_bf16_f32 v141, v134, v135
	v_cvt_pk_bf16_f32 v142, v136, v137
	v_cvt_pk_bf16_f32 v143, v138, v139
	global_store_dwordx4 v173, v[140:143], s[4:5] offset:0 nt
	v_pk_mul_f32 v[132:133], v[58:59], v[130:131]
	v_pk_mul_f32 v[134:135], v[60:61], v[130:131]
	v_pk_mul_f32 v[136:137], v[14:15], v[130:131]
	v_pk_mul_f32 v[138:139], v[16:17], v[130:131]
	v_exp_f32_e32 v132, v132
	v_exp_f32_e32 v133, v133
	v_exp_f32_e32 v134, v134
	v_exp_f32_e32 v135, v135
	v_exp_f32_e32 v136, v136
	v_exp_f32_e32 v137, v137
	v_exp_f32_e32 v138, v138
	v_exp_f32_e32 v139, v139
	v_pk_add_f32 v[132:133], v[132:133], 1.0 op_sel_hi:[1,0]
	v_pk_add_f32 v[134:135], v[134:135], 1.0 op_sel_hi:[1,0]
	v_pk_add_f32 v[136:137], v[136:137], 1.0 op_sel_hi:[1,0]
	v_pk_add_f32 v[138:139], v[138:139], 1.0 op_sel_hi:[1,0]
	v_rcp_f32_e32 v132, v132
	v_rcp_f32_e32 v133, v133
	v_rcp_f32_e32 v134, v134
	v_rcp_f32_e32 v135, v135
	v_rcp_f32_e32 v136, v136
	v_rcp_f32_e32 v137, v137
	v_rcp_f32_e32 v138, v138
	v_rcp_f32_e32 v139, v139
	v_pk_mul_f32 v[132:133], v[58:59], v[132:133]
	v_pk_mul_f32 v[134:135], v[60:61], v[134:135]
	v_pk_mul_f32 v[136:137], v[14:15], v[136:137]
	v_pk_mul_f32 v[138:139], v[16:17], v[138:139]
	v_cvt_pk_bf16_f32 v144, v132, v133
	v_cvt_pk_bf16_f32 v145, v134, v135
	v_cvt_pk_bf16_f32 v146, v136, v137
	v_cvt_pk_bf16_f32 v147, v138, v139
	global_store_dwordx4 v173, v[144:147], s[4:5] offset:256 nt
	s_add_u32 s4, s14, 147456
	s_addc_u32 s5, s15, 0
	v_pk_mul_f32 v[132:133], v[26:27], v[130:131]
	v_pk_mul_f32 v[134:135], v[28:29], v[130:131]
	v_pk_mul_f32 v[136:137], v[54:55], v[130:131]
	v_pk_mul_f32 v[138:139], v[56:57], v[130:131]
	v_exp_f32_e32 v132, v132
	v_exp_f32_e32 v133, v133
	v_exp_f32_e32 v134, v134
	v_exp_f32_e32 v135, v135
	v_exp_f32_e32 v136, v136
	v_exp_f32_e32 v137, v137
	v_exp_f32_e32 v138, v138
	v_exp_f32_e32 v139, v139
	v_pk_add_f32 v[132:133], v[132:133], 1.0 op_sel_hi:[1,0]
	v_pk_add_f32 v[134:135], v[134:135], 1.0 op_sel_hi:[1,0]
	v_pk_add_f32 v[136:137], v[136:137], 1.0 op_sel_hi:[1,0]
	v_pk_add_f32 v[138:139], v[138:139], 1.0 op_sel_hi:[1,0]
	v_rcp_f32_e32 v132, v132
	v_rcp_f32_e32 v133, v133
	v_rcp_f32_e32 v134, v134
	v_rcp_f32_e32 v135, v135
	v_rcp_f32_e32 v136, v136
	v_rcp_f32_e32 v137, v137
	v_rcp_f32_e32 v138, v138
	v_rcp_f32_e32 v139, v139
	v_pk_mul_f32 v[132:133], v[26:27], v[132:133]
	v_pk_mul_f32 v[134:135], v[28:29], v[134:135]
	v_pk_mul_f32 v[136:137], v[54:55], v[136:137]
	v_pk_mul_f32 v[138:139], v[56:57], v[138:139]
	v_cvt_pk_bf16_f32 v140, v132, v133
	v_cvt_pk_bf16_f32 v141, v134, v135
	v_cvt_pk_bf16_f32 v142, v136, v137
	v_cvt_pk_bf16_f32 v143, v138, v139
	global_store_dwordx4 v173, v[140:143], s[4:5] offset:0 nt
	v_pk_mul_f32 v[132:133], v[50:51], v[130:131]
	v_pk_mul_f32 v[134:135], v[52:53], v[130:131]
	v_pk_mul_f32 v[136:137], v[10:11], v[130:131]
	v_pk_mul_f32 v[138:139], v[12:13], v[130:131]
	v_exp_f32_e32 v132, v132
	v_exp_f32_e32 v133, v133
	v_exp_f32_e32 v134, v134
	v_exp_f32_e32 v135, v135
	v_exp_f32_e32 v136, v136
	v_exp_f32_e32 v137, v137
	v_exp_f32_e32 v138, v138
	v_exp_f32_e32 v139, v139
	v_pk_add_f32 v[132:133], v[132:133], 1.0 op_sel_hi:[1,0]
	v_pk_add_f32 v[134:135], v[134:135], 1.0 op_sel_hi:[1,0]
	v_pk_add_f32 v[136:137], v[136:137], 1.0 op_sel_hi:[1,0]
	v_pk_add_f32 v[138:139], v[138:139], 1.0 op_sel_hi:[1,0]
	v_rcp_f32_e32 v132, v132
	v_rcp_f32_e32 v133, v133
	v_rcp_f32_e32 v134, v134
	v_rcp_f32_e32 v135, v135
	v_rcp_f32_e32 v136, v136
	v_rcp_f32_e32 v137, v137
	v_rcp_f32_e32 v138, v138
	v_rcp_f32_e32 v139, v139
	v_pk_mul_f32 v[132:133], v[50:51], v[132:133]
	v_pk_mul_f32 v[134:135], v[52:53], v[134:135]
	v_pk_mul_f32 v[136:137], v[10:11], v[136:137]
	v_pk_mul_f32 v[138:139], v[12:13], v[138:139]
	v_cvt_pk_bf16_f32 v144, v132, v133
	v_cvt_pk_bf16_f32 v145, v134, v135
	v_cvt_pk_bf16_f32 v146, v136, v137
	v_cvt_pk_bf16_f32 v147, v138, v139
	global_store_dwordx4 v173, v[144:147], s[4:5] offset:256 nt
	s_add_u32 s4, s14, 163840
	s_addc_u32 s5, s15, 0
	v_pk_mul_f32 v[132:133], v[22:23], v[130:131]
	v_pk_mul_f32 v[134:135], v[24:25], v[130:131]
	v_pk_mul_f32 v[136:137], v[46:47], v[130:131]
	v_pk_mul_f32 v[138:139], v[48:49], v[130:131]
	v_exp_f32_e32 v132, v132
	v_exp_f32_e32 v133, v133
	v_exp_f32_e32 v134, v134
	v_exp_f32_e32 v135, v135
	v_exp_f32_e32 v136, v136
	v_exp_f32_e32 v137, v137
	v_exp_f32_e32 v138, v138
	v_exp_f32_e32 v139, v139
	v_pk_add_f32 v[132:133], v[132:133], 1.0 op_sel_hi:[1,0]
	v_pk_add_f32 v[134:135], v[134:135], 1.0 op_sel_hi:[1,0]
	v_pk_add_f32 v[136:137], v[136:137], 1.0 op_sel_hi:[1,0]
	v_pk_add_f32 v[138:139], v[138:139], 1.0 op_sel_hi:[1,0]
	v_rcp_f32_e32 v132, v132
	v_rcp_f32_e32 v133, v133
	v_rcp_f32_e32 v134, v134
	v_rcp_f32_e32 v135, v135
	v_rcp_f32_e32 v136, v136
	v_rcp_f32_e32 v137, v137
	v_rcp_f32_e32 v138, v138
	v_rcp_f32_e32 v139, v139
	v_pk_mul_f32 v[132:133], v[22:23], v[132:133]
	v_pk_mul_f32 v[134:135], v[24:25], v[134:135]
	v_pk_mul_f32 v[136:137], v[46:47], v[136:137]
	v_pk_mul_f32 v[138:139], v[48:49], v[138:139]
	v_cvt_pk_bf16_f32 v140, v132, v133
	v_cvt_pk_bf16_f32 v141, v134, v135
	v_cvt_pk_bf16_f32 v142, v136, v137
	v_cvt_pk_bf16_f32 v143, v138, v139
	global_store_dwordx4 v173, v[140:143], s[4:5] offset:0 nt
	v_pk_mul_f32 v[132:133], v[42:43], v[130:131]
	v_pk_mul_f32 v[134:135], v[44:45], v[130:131]
	v_pk_mul_f32 v[136:137], v[6:7], v[130:131]
	v_pk_mul_f32 v[138:139], v[8:9], v[130:131]
;     __device__ __forceinline__ void operator()(const f32x4 (&acc)[2][2][4][2], const pg8::Unit& u, int wr, int wc, int fr, int fq) const {
;     ...
;             bf16_t* G = (bf16_t*)(ws + WS_G);
;             const int chb = 128 * (pn - 10) + 16 * wc + 4 * fq;
;             const int odd = fq & 1;
; #pragma unroll
;             for (int ai = 0; ai < 2; ++ai)
; #pragma unroll
;                 for (int mp = 0; mp < 2; ++mp) {
;                     const size_t row = (size_t)(row0 + ai * 128 + (2 * mp + odd) * 16);
; #pragma unroll
;                     for (int bj = 0; bj < 2; ++bj) {
;                         const f32x4 ua = acc[ai][bj][2 * mp][0], ga = acc[ai][bj][2 * mp][1], ub = acc[ai][bj][2 * mp + 1][0], gb = acc[ai][bj][2 * mp + 1][1];
;                         const unsigned a0 = cvt_pk_bf16(ua[0] * sigmoidf_(ga[0]), ua[1] * sigmoidf_(ga[1])), a1 = cvt_pk_bf16(ua[2] * sigmoidf_(ga[2]), ua[3] * sigmoidf_(ga[3]));
;                         const unsigned b0 = cvt_pk_bf16(ub[0] * sigmoidf_(gb[0]), ub[1] * sigmoidf_(gb[1])), b1 = cvt_pk_bf16(ub[2] * sigmoidf_(gb[2]), ub[3] * sigmoidf_(gb[3]));
;                         asm volatile("s_nop 1" ::: "memory");
;                         const u32x2 s0 = __builtin_amdgcn_permlane16_swap(a0, b0, false, false), s1 = __builtin_amdgcn_permlane16_swap(a1, b1, false, false);
;                         *(u32x4*)(G + row * 512 + (chb - 4 * odd) + 64 * bj) = (u32x4){s0[0], s1[0], s0[1], s1[1]};
;                     }
;     ...
;             bf16_t* D = (bf16_t*)(ws + (pn < 10 ? WS_GA : WS_GB));
;             const int colb = 256 * (pn < 10 ? pn - 8 : pn - 14) + 32 * wc + 8 * fq;
; #pragma unroll
;             for (int ai = 0; ai < 2; ++ai)
; #pragma unroll
;                 for (int m = 0; m < 4; ++m) {
;                     const size_t row = (size_t)(row0 + ai * 128 + m * 16);
; #pragma unroll
;                     for (int bj = 0; bj < 2; ++bj) {
;                         f32x4 v0 = acc[ai][bj][m][0], v1 = acc[ai][bj][m][1];
; #pragma unroll
;                         for (int j = 0; j < 4; ++j) { v0[j] = siluf_(v0[j]); v1[j] = siluf_(v1[j]); }
;                         u32x4 o = {cvt_pk_bf16(v0[0], v0[1]), cvt_pk_bf16(v0[2], v0[3]), cvt_pk_bf16(v1[0], v1[1]), cvt_pk_bf16(v1[2], v1[3])};
;                         *(u32x4*)(D + row * 512 + colb + 128 * bj) = o;
;                     }
	v_exp_f32_e32 v132, v132
	v_exp_f32_e32 v133, v133
	v_exp_f32_e32 v134, v134
	v_exp_f32_e32 v135, v135
	v_exp_f32_e32 v136, v136
	v_exp_f32_e32 v137, v137
	v_exp_f32_e32 v138, v138
	v_exp_f32_e32 v139, v139
	v_pk_add_f32 v[132:133], v[132:133], 1.0 op_sel_hi:[1,0]
	v_pk_add_f32 v[134:135], v[134:135], 1.0 op_sel_hi:[1,0]
	v_pk_add_f32 v[136:137], v[136:137], 1.0 op_sel_hi:[1,0]
	v_pk_add_f32 v[138:139], v[138:139], 1.0 op_sel_hi:[1,0]
	v_rcp_f32_e32 v132, v132
	v_rcp_f32_e32 v133, v133
	v_rcp_f32_e32 v134, v134
	v_rcp_f32_e32 v135, v135
	v_rcp_f32_e32 v136, v136
	v_rcp_f32_e32 v137, v137
	v_rcp_f32_e32 v138, v138
	v_rcp_f32_e32 v139, v139
	v_pk_mul_f32 v[132:133], v[42:43], v[132:133]
	v_pk_mul_f32 v[134:135], v[44:45], v[134:135]
	v_pk_mul_f32 v[136:137], v[6:7], v[136:137]
	v_pk_mul_f32 v[138:139], v[8:9], v[138:139]
	v_cvt_pk_bf16_f32 v144, v132, v133
	v_cvt_pk_bf16_f32 v145, v134, v135
	v_cvt_pk_bf16_f32 v146, v136, v137
	v_cvt_pk_bf16_f32 v147, v138, v139
	global_store_dwordx4 v173, v[144:147], s[4:5] offset:256 nt
	s_add_u32 s4, s14, 180224
	s_addc_u32 s5, s15, 0
	v_pk_mul_f32 v[132:133], v[18:19], v[130:131]
	v_pk_mul_f32 v[134:135], v[20:21], v[130:131]
	v_pk_mul_f32 v[136:137], v[38:39], v[130:131]
	v_pk_mul_f32 v[138:139], v[40:41], v[130:131]
	v_exp_f32_e32 v132, v132
	v_exp_f32_e32 v133, v133
	v_exp_f32_e32 v134, v134
	v_exp_f32_e32 v135, v135
	v_exp_f32_e32 v136, v136
	v_exp_f32_e32 v137, v137
	v_exp_f32_e32 v138, v138
	v_exp_f32_e32 v139, v139
	v_pk_add_f32 v[132:133], v[132:133], 1.0 op_sel_hi:[1,0]
	v_pk_add_f32 v[134:135], v[134:135], 1.0 op_sel_hi:[1,0]
	v_pk_add_f32 v[136:137], v[136:137], 1.0 op_sel_hi:[1,0]
	v_pk_add_f32 v[138:139], v[138:139], 1.0 op_sel_hi:[1,0]
	v_rcp_f32_e32 v132, v132
	v_rcp_f32_e32 v133, v133
	v_rcp_f32_e32 v134, v134
	v_rcp_f32_e32 v135, v135
	v_rcp_f32_e32 v136, v136
	v_rcp_f32_e32 v137, v137
	v_rcp_f32_e32 v138, v138
	v_rcp_f32_e32 v139, v139
	v_pk_mul_f32 v[132:133], v[18:19], v[132:133]
	v_pk_mul_f32 v[134:135], v[20:21], v[134:135]
	v_pk_mul_f32 v[136:137], v[38:39], v[136:137]
	v_pk_mul_f32 v[138:139], v[40:41], v[138:139]
	v_cvt_pk_bf16_f32 v140, v132, v133
	v_cvt_pk_bf16_f32 v141, v134, v135
	v_cvt_pk_bf16_f32 v142, v136, v137
	v_cvt_pk_bf16_f32 v143, v138, v139
	global_store_dwordx4 v173, v[140:143], s[4:5] offset:0 nt
	v_pk_mul_f32 v[132:133], v[34:35], v[130:131]
	v_pk_mul_f32 v[134:135], v[36:37], v[130:131]
	v_pk_mul_f32 v[136:137], v[2:3], v[130:131]
	v_pk_mul_f32 v[138:139], v[4:5], v[130:131]
	v_exp_f32_e32 v132, v132
	v_exp_f32_e32 v133, v133
	v_exp_f32_e32 v134, v134
	v_exp_f32_e32 v135, v135
	v_exp_f32_e32 v136, v136
	v_exp_f32_e32 v137, v137
	v_exp_f32_e32 v138, v138
	v_exp_f32_e32 v139, v139
	v_pk_add_f32 v[132:133], v[132:133], 1.0 op_sel_hi:[1,0]
	v_pk_add_f32 v[134:135], v[134:135], 1.0 op_sel_hi:[1,0]
	v_pk_add_f32 v[136:137], v[136:137], 1.0 op_sel_hi:[1,0]
	v_pk_add_f32 v[138:139], v[138:139], 1.0 op_sel_hi:[1,0]
	v_rcp_f32_e32 v132, v132
	v_rcp_f32_e32 v133, v133
	v_rcp_f32_e32 v134, v134
	v_rcp_f32_e32 v135, v135
	v_rcp_f32_e32 v136, v136
	v_rcp_f32_e32 v137, v137
	v_rcp_f32_e32 v138, v138
	v_rcp_f32_e32 v139, v139
	v_pk_mul_f32 v[132:133], v[34:35], v[132:133]
	v_pk_mul_f32 v[134:135], v[36:37], v[134:135]
	v_pk_mul_f32 v[136:137], v[2:3], v[136:137]
	v_pk_mul_f32 v[138:139], v[4:5], v[138:139]
	v_cvt_pk_bf16_f32 v144, v132, v133
	v_cvt_pk_bf16_f32 v145, v134, v135
	v_cvt_pk_bf16_f32 v146, v136, v137
	v_cvt_pk_bf16_f32 v147, v138, v139
	global_store_dwordx4 v173, v[144:147], s[4:5] offset:256 nt
	s_branch .LBB0_187
.LBB0_188:
	s_add_i32 s4, s10, -10
	s_cmp_gt_u32 s4, 3
	s_cbranch_scc1 .Lgate_new
	s_add_u32 s14, s70, 0x11b00000
	s_addc_u32 s15, s71, 0
	v_lshl_add_u32 v173, s10, 7, v184
	v_lshlrev_b32_e32 v173, 1, v173
	v_or_b32_e32 v132, v172, v178
	v_lshl_add_u32 v173, v132, 10, v173
	v_mov_b32_e32 v130, 0xbfb8aa3b
	v_mov_b32_e32 v131, 0xbfb8aa3b
	s_add_u32 s4, s14, 0
	s_addc_u32 s5, s15, 0
	v_pk_mul_f32 v[132:133], v[126:127], v[130:131]
	v_pk_mul_f32 v[134:135], v[128:129], v[130:131]
	v_pk_mul_f32 v[136:137], v[118:119], v[130:131]
	v_pk_mul_f32 v[138:139], v[120:121], v[130:131]
	v_exp_f32_e32 v132, v132
	v_exp_f32_e32 v133, v133
	v_exp_f32_e32 v134, v134
	v_exp_f32_e32 v135, v135
	v_exp_f32_e32 v136, v136
	v_exp_f32_e32 v137, v137
	v_exp_f32_e32 v138, v138
	v_exp_f32_e32 v139, v139
	v_pk_add_f32 v[132:133], v[132:133], 1.0 op_sel_hi:[1,0]
	v_pk_add_f32 v[134:135], v[134:135], 1.0 op_sel_hi:[1,0]
	v_pk_add_f32 v[136:137], v[136:137], 1.0 op_sel_hi:[1,0]
	v_pk_add_f32 v[138:139], v[138:139], 1.0 op_sel_hi:[1,0]
	v_rcp_f32_e32 v132, v132
	v_rcp_f32_e32 v133, v133
	v_rcp_f32_e32 v134, v134
	v_rcp_f32_e32 v135, v135
	v_rcp_f32_e32 v136, v136
	v_rcp_f32_e32 v137, v137
	v_rcp_f32_e32 v138, v138
	v_rcp_f32_e32 v139, v139
	v_pk_mul_f32 v[132:133], v[94:95], v[132:133]
	v_pk_mul_f32 v[134:135], v[96:97], v[134:135]
	v_pk_mul_f32 v[136:137], v[90:91], v[136:137]
	v_pk_mul_f32 v[138:139], v[92:93], v[138:139]
	v_cvt_pk_bf16_f32 v140, v132, v133
	v_cvt_pk_bf16_f32 v141, v134, v135
	v_cvt_pk_bf16_f32 v142, v136, v137
	v_cvt_pk_bf16_f32 v143, v138, v139
	s_nop 1
	v_permlane16_swap_b32_e32 v140, v142
	v_permlane16_swap_b32_e32 v141, v143
	s_nop 1
	global_store_dwordx4 v173, v[140:143], s[4:5] offset:0 nt
	v_pk_mul_f32 v[132:133], v[78:79], v[130:131]
	v_pk_mul_f32 v[134:135], v[80:81], v[130:131]
	v_pk_mul_f32 v[136:137], v[74:75], v[130:131]
	v_pk_mul_f32 v[138:139], v[76:77], v[130:131]
	v_exp_f32_e32 v132, v132
	v_exp_f32_e32 v133, v133
	v_exp_f32_e32 v134, v134
	v_exp_f32_e32 v135, v135
	v_exp_f32_e32 v136, v136
	v_exp_f32_e32 v137, v137
	v_exp_f32_e32 v138, v138
; __device__ __forceinline__ unsigned cvt_pk_bf16(float lo, float hi) { unsigned r; asm volatile("v_cvt_pk_bf16_f32 %0, %1, %2" : "=v"(r) : "v"(lo), "v"(hi)); return r; }
; __device__ __forceinline__ float sigmoidf_(float v) { return __builtin_amdgcn_rcpf(1.f + __expf(-v)); }
;     __device__ __forceinline__ void operator()(const f32x4 (&acc)[2][2][4][2], const pg8::Unit& u, int wr, int wc, int fr, int fq) const {
;     ...
;             bf16_t* G = (bf16_t*)(ws + WS_G);
;             const int chb = 128 * (pn - 10) + 16 * wc + 4 * fq;
;             const int odd = fq & 1;
; #pragma unroll
;             for (int ai = 0; ai < 2; ++ai)
; #pragma unroll
;                 for (int mp = 0; mp < 2; ++mp) {
;                     const size_t row = (size_t)(row0 + ai * 128 + (2 * mp + odd) * 16);
; #pragma unroll
;                     for (int bj = 0; bj < 2; ++bj) {
;                         const f32x4 ua = acc[ai][bj][2 * mp][0], ga = acc[ai][bj][2 * mp][1], ub = acc[ai][bj][2 * mp + 1][0], gb = acc[ai][bj][2 * mp + 1][1];
;                         const unsigned a0 = cvt_pk_bf16(ua[0] * sigmoidf_(ga[0]), ua[1] * sigmoidf_(ga[1])), a1 = cvt_pk_bf16(ua[2] * sigmoidf_(ga[2]), ua[3] * sigmoidf_(ga[3]));
;                         const unsigned b0 = cvt_pk_bf16(ub[0] * sigmoidf_(gb[0]), ub[1] * sigmoidf_(gb[1])), b1 = cvt_pk_bf16(ub[2] * sigmoidf_(gb[2]), ub[3] * sigmoidf_(gb[3]));
;                         asm volatile("s_nop 1" ::: "memory");
;                         const u32x2 s0 = __builtin_amdgcn_permlane16_swap(a0, b0, false, false), s1 = __builtin_amdgcn_permlane16_swap(a1, b1, false, false);
;                         *(u32x4*)(G + row * 512 + (chb - 4 * odd) + 64 * bj) = (u32x4){s0[0], s1[0], s0[1], s1[1]};
;                     }
	v_exp_f32_e32 v139, v139
	v_pk_add_f32 v[132:133], v[132:133], 1.0 op_sel_hi:[1,0]
	v_pk_add_f32 v[134:135], v[134:135], 1.0 op_sel_hi:[1,0]
	v_pk_add_f32 v[136:137], v[136:137], 1.0 op_sel_hi:[1,0]
	v_pk_add_f32 v[138:139], v[138:139], 1.0 op_sel_hi:[1,0]
	v_rcp_f32_e32 v132, v132
	v_rcp_f32_e32 v133, v133
	v_rcp_f32_e32 v134, v134
	v_rcp_f32_e32 v135, v135
	v_rcp_f32_e32 v136, v136
	v_rcp_f32_e32 v137, v137
	v_rcp_f32_e32 v138, v138
	v_rcp_f32_e32 v139, v139
	v_pk_mul_f32 v[132:133], v[122:123], v[132:133]
	v_pk_mul_f32 v[134:135], v[124:125], v[134:135]
	v_pk_mul_f32 v[136:137], v[114:115], v[136:137]
	v_pk_mul_f32 v[138:139], v[116:117], v[138:139]
	v_cvt_pk_bf16_f32 v144, v132, v133
	v_cvt_pk_bf16_f32 v145, v134, v135
	v_cvt_pk_bf16_f32 v146, v136, v137
	v_cvt_pk_bf16_f32 v147, v138, v139
	s_nop 1
	v_permlane16_swap_b32_e32 v144, v146
	v_permlane16_swap_b32_e32 v145, v147
	s_nop 1
	global_store_dwordx4 v173, v[144:147], s[4:5] offset:128 nt
	s_add_u32 s4, s14, 32768
	s_addc_u32 s5, s15, 0
	v_pk_mul_f32 v[132:133], v[110:111], v[130:131]
	v_pk_mul_f32 v[134:135], v[112:113], v[130:131]
	v_pk_mul_f32 v[136:137], v[102:103], v[130:131]
	v_pk_mul_f32 v[138:139], v[104:105], v[130:131]
	v_exp_f32_e32 v132, v132
	v_exp_f32_e32 v133, v133
	v_exp_f32_e32 v134, v134
	v_exp_f32_e32 v135, v135
	v_exp_f32_e32 v136, v136
	v_exp_f32_e32 v137, v137
	v_exp_f32_e32 v138, v138
	v_exp_f32_e32 v139, v139
	v_pk_add_f32 v[132:133], v[132:133], 1.0 op_sel_hi:[1,0]
	v_pk_add_f32 v[134:135], v[134:135], 1.0 op_sel_hi:[1,0]
	v_pk_add_f32 v[136:137], v[136:137], 1.0 op_sel_hi:[1,0]
	v_pk_add_f32 v[138:139], v[138:139], 1.0 op_sel_hi:[1,0]
	v_rcp_f32_e32 v132, v132
	v_rcp_f32_e32 v133, v133
	v_rcp_f32_e32 v134, v134
	v_rcp_f32_e32 v135, v135
	v_rcp_f32_e32 v136, v136
	v_rcp_f32_e32 v137, v137
	v_rcp_f32_e32 v138, v138
	v_rcp_f32_e32 v139, v139
	v_pk_mul_f32 v[132:133], v[86:87], v[132:133]
	v_pk_mul_f32 v[134:135], v[88:89], v[134:135]
	v_pk_mul_f32 v[136:137], v[82:83], v[136:137]
	v_pk_mul_f32 v[138:139], v[84:85], v[138:139]
	v_cvt_pk_bf16_f32 v140, v132, v133
	v_cvt_pk_bf16_f32 v141, v134, v135
	v_cvt_pk_bf16_f32 v142, v136, v137
	v_cvt_pk_bf16_f32 v143, v138, v139
	s_nop 1
	v_permlane16_swap_b32_e32 v140, v142
	v_permlane16_swap_b32_e32 v141, v143
	s_nop 1
	global_store_dwordx4 v173, v[140:143], s[4:5] offset:0 nt
	v_pk_mul_f32 v[132:133], v[70:71], v[130:131]
	v_pk_mul_f32 v[134:135], v[72:73], v[130:131]
	v_pk_mul_f32 v[136:137], v[66:67], v[130:131]
	v_pk_mul_f32 v[138:139], v[68:69], v[130:131]
	v_exp_f32_e32 v132, v132
	v_exp_f32_e32 v133, v133
	v_exp_f32_e32 v134, v134
	v_exp_f32_e32 v135, v135
	v_exp_f32_e32 v136, v136
	v_exp_f32_e32 v137, v137
	v_exp_f32_e32 v138, v138
	v_exp_f32_e32 v139, v139
	v_pk_add_f32 v[132:133], v[132:133], 1.0 op_sel_hi:[1,0]
	v_pk_add_f32 v[134:135], v[134:135], 1.0 op_sel_hi:[1,0]
	v_pk_add_f32 v[136:137], v[136:137], 1.0 op_sel_hi:[1,0]
	v_pk_add_f32 v[138:139], v[138:139], 1.0 op_sel_hi:[1,0]
	v_rcp_f32_e32 v132, v132
	v_rcp_f32_e32 v133, v133
	v_rcp_f32_e32 v134, v134
	v_rcp_f32_e32 v135, v135
	v_rcp_f32_e32 v136, v136
	v_rcp_f32_e32 v137, v137
	v_rcp_f32_e32 v138, v138
	v_rcp_f32_e32 v139, v139
	v_pk_mul_f32 v[132:133], v[106:107], v[132:133]
	v_pk_mul_f32 v[134:135], v[108:109], v[134:135]
	v_pk_mul_f32 v[136:137], v[98:99], v[136:137]
	v_pk_mul_f32 v[138:139], v[100:101], v[138:139]
	v_cvt_pk_bf16_f32 v144, v132, v133
	v_cvt_pk_bf16_f32 v145, v134, v135
	v_cvt_pk_bf16_f32 v146, v136, v137
	v_cvt_pk_bf16_f32 v147, v138, v139
	s_nop 1
	v_permlane16_swap_b32_e32 v144, v146
	v_permlane16_swap_b32_e32 v145, v147
	s_nop 1
	global_store_dwordx4 v173, v[144:147], s[4:5] offset:128 nt
	s_add_u32 s4, s14, 131072
	s_addc_u32 s5, s15, 0
	v_pk_mul_f32 v[132:133], v[62:63], v[130:131]
	v_pk_mul_f32 v[134:135], v[64:65], v[130:131]
	v_pk_mul_f32 v[136:137], v[54:55], v[130:131]
	v_pk_mul_f32 v[138:139], v[56:57], v[130:131]
	v_exp_f32_e32 v132, v132
	v_exp_f32_e32 v133, v133
	v_exp_f32_e32 v134, v134
	v_exp_f32_e32 v135, v135
	v_exp_f32_e32 v136, v136
	v_exp_f32_e32 v137, v137
	v_exp_f32_e32 v138, v138
	v_exp_f32_e32 v139, v139
	v_pk_add_f32 v[132:133], v[132:133], 1.0 op_sel_hi:[1,0]
	v_pk_add_f32 v[134:135], v[134:135], 1.0 op_sel_hi:[1,0]
	v_pk_add_f32 v[136:137], v[136:137], 1.0 op_sel_hi:[1,0]
	v_pk_add_f32 v[138:139], v[138:139], 1.0 op_sel_hi:[1,0]
	v_rcp_f32_e32 v132, v132
	v_rcp_f32_e32 v133, v133
	v_rcp_f32_e32 v134, v134
	v_rcp_f32_e32 v135, v135
	v_rcp_f32_e32 v136, v136
	v_rcp_f32_e32 v137, v137
	v_rcp_f32_e32 v138, v138
; __device__ __forceinline__ unsigned cvt_pk_bf16(float lo, float hi) { unsigned r; asm volatile("v_cvt_pk_bf16_f32 %0, %1, %2" : "=v"(r) : "v"(lo), "v"(hi)); return r; }
; __device__ __forceinline__ float sigmoidf_(float v) { return __builtin_amdgcn_rcpf(1.f + __expf(-v)); }
;     __device__ __forceinline__ void operator()(const f32x4 (&acc)[2][2][4][2], const pg8::Unit& u, int wr, int wc, int fr, int fq) const {
;     ...
;             bf16_t* G = (bf16_t*)(ws + WS_G);
;             const int chb = 128 * (pn - 10) + 16 * wc + 4 * fq;
;             const int odd = fq & 1;
; #pragma unroll
;             for (int ai = 0; ai < 2; ++ai)
; #pragma unroll
;                 for (int mp = 0; mp < 2; ++mp) {
;                     const size_t row = (size_t)(row0 + ai * 128 + (2 * mp + odd) * 16);
; #pragma unroll
;                     for (int bj = 0; bj < 2; ++bj) {
;                         const f32x4 ua = acc[ai][bj][2 * mp][0], ga = acc[ai][bj][2 * mp][1], ub = acc[ai][bj][2 * mp + 1][0], gb = acc[ai][bj][2 * mp + 1][1];
;                         const unsigned a0 = cvt_pk_bf16(ua[0] * sigmoidf_(ga[0]), ua[1] * sigmoidf_(ga[1])), a1 = cvt_pk_bf16(ua[2] * sigmoidf_(ga[2]), ua[3] * sigmoidf_(ga[3]));
;                         const unsigned b0 = cvt_pk_bf16(ub[0] * sigmoidf_(gb[0]), ub[1] * sigmoidf_(gb[1])), b1 = cvt_pk_bf16(ub[2] * sigmoidf_(gb[2]), ub[3] * sigmoidf_(gb[3]));
;                         asm volatile("s_nop 1" ::: "memory");
;                         const u32x2 s0 = __builtin_amdgcn_permlane16_swap(a0, b0, false, false), s1 = __builtin_amdgcn_permlane16_swap(a1, b1, false, false);
;                         *(u32x4*)(G + row * 512 + (chb - 4 * odd) + 64 * bj) = (u32x4){s0[0], s1[0], s0[1], s1[1]};
;                     }
	v_rcp_f32_e32 v139, v139
	v_pk_mul_f32 v[132:133], v[30:31], v[132:133]
	v_pk_mul_f32 v[134:135], v[32:33], v[134:135]
	v_pk_mul_f32 v[136:137], v[26:27], v[136:137]
	v_pk_mul_f32 v[138:139], v[28:29], v[138:139]
	v_cvt_pk_bf16_f32 v140, v132, v133
	v_cvt_pk_bf16_f32 v141, v134, v135
	v_cvt_pk_bf16_f32 v142, v136, v137
	v_cvt_pk_bf16_f32 v143, v138, v139
	s_nop 1
	v_permlane16_swap_b32_e32 v140, v142
	v_permlane16_swap_b32_e32 v141, v143
	s_nop 1
	global_store_dwordx4 v173, v[140:143], s[4:5] offset:0 nt
	v_pk_mul_f32 v[132:133], v[14:15], v[130:131]
	v_pk_mul_f32 v[134:135], v[16:17], v[130:131]
	v_pk_mul_f32 v[136:137], v[10:11], v[130:131]
	v_pk_mul_f32 v[138:139], v[12:13], v[130:131]
	v_exp_f32_e32 v132, v132
	v_exp_f32_e32 v133, v133
	v_exp_f32_e32 v134, v134
	v_exp_f32_e32 v135, v135
	v_exp_f32_e32 v136, v136
	v_exp_f32_e32 v137, v137
	v_exp_f32_e32 v138, v138
	v_exp_f32_e32 v139, v139
	v_pk_add_f32 v[132:133], v[132:133], 1.0 op_sel_hi:[1,0]
	v_pk_add_f32 v[134:135], v[134:135], 1.0 op_sel_hi:[1,0]
	v_pk_add_f32 v[136:137], v[136:137], 1.0 op_sel_hi:[1,0]
	v_pk_add_f32 v[138:139], v[138:139], 1.0 op_sel_hi:[1,0]
	v_rcp_f32_e32 v132, v132
	v_rcp_f32_e32 v133, v133
	v_rcp_f32_e32 v134, v134
	v_rcp_f32_e32 v135, v135
	v_rcp_f32_e32 v136, v136
	v_rcp_f32_e32 v137, v137
	v_rcp_f32_e32 v138, v138
	v_rcp_f32_e32 v139, v139
	v_pk_mul_f32 v[132:133], v[58:59], v[132:133]
	v_pk_mul_f32 v[134:135], v[60:61], v[134:135]
	v_pk_mul_f32 v[136:137], v[50:51], v[136:137]
	v_pk_mul_f32 v[138:139], v[52:53], v[138:139]
	v_cvt_pk_bf16_f32 v144, v132, v133
	v_cvt_pk_bf16_f32 v145, v134, v135
	v_cvt_pk_bf16_f32 v146, v136, v137
	v_cvt_pk_bf16_f32 v147, v138, v139
	s_nop 1
	v_permlane16_swap_b32_e32 v144, v146
	v_permlane16_swap_b32_e32 v145, v147
	s_nop 1
	global_store_dwordx4 v173, v[144:147], s[4:5] offset:128 nt
	s_add_u32 s4, s14, 163840
	s_addc_u32 s5, s15, 0
	v_pk_mul_f32 v[132:133], v[46:47], v[130:131]
	v_pk_mul_f32 v[134:135], v[48:49], v[130:131]
	v_pk_mul_f32 v[136:137], v[38:39], v[130:131]
	v_pk_mul_f32 v[138:139], v[40:41], v[130:131]
	v_exp_f32_e32 v132, v132
	v_exp_f32_e32 v133, v133
	v_exp_f32_e32 v134, v134
	v_exp_f32_e32 v135, v135
	v_exp_f32_e32 v136, v136
	v_exp_f32_e32 v137, v137
	v_exp_f32_e32 v138, v138
	v_exp_f32_e32 v139, v139
	v_pk_add_f32 v[132:133], v[132:133], 1.0 op_sel_hi:[1,0]
	v_pk_add_f32 v[134:135], v[134:135], 1.0 op_sel_hi:[1,0]
	v_pk_add_f32 v[136:137], v[136:137], 1.0 op_sel_hi:[1,0]
	v_pk_add_f32 v[138:139], v[138:139], 1.0 op_sel_hi:[1,0]
	v_rcp_f32_e32 v132, v132
	v_rcp_f32_e32 v133, v133
	v_rcp_f32_e32 v134, v134
	v_rcp_f32_e32 v135, v135
	v_rcp_f32_e32 v136, v136
	v_rcp_f32_e32 v137, v137
	v_rcp_f32_e32 v138, v138
	v_rcp_f32_e32 v139, v139
	v_pk_mul_f32 v[132:133], v[22:23], v[132:133]
	v_pk_mul_f32 v[134:135], v[24:25], v[134:135]
	v_pk_mul_f32 v[136:137], v[18:19], v[136:137]
	v_pk_mul_f32 v[138:139], v[20:21], v[138:139]
	v_cvt_pk_bf16_f32 v140, v132, v133
	v_cvt_pk_bf16_f32 v141, v134, v135
	v_cvt_pk_bf16_f32 v142, v136, v137
	v_cvt_pk_bf16_f32 v143, v138, v139
	s_nop 1
	v_permlane16_swap_b32_e32 v140, v142
	v_permlane16_swap_b32_e32 v141, v143
	s_nop 1
	global_store_dwordx4 v173, v[140:143], s[4:5] offset:0 nt
	v_pk_mul_f32 v[132:133], v[6:7], v[130:131]
	v_pk_mul_f32 v[134:135], v[8:9], v[130:131]
	v_pk_mul_f32 v[136:137], v[2:3], v[130:131]
	v_pk_mul_f32 v[138:139], v[4:5], v[130:131]
	v_exp_f32_e32 v132, v132
	v_exp_f32_e32 v133, v133
	v_exp_f32_e32 v134, v134
	v_exp_f32_e32 v135, v135
	v_exp_f32_e32 v136, v136
	v_exp_f32_e32 v137, v137
	v_exp_f32_e32 v138, v138
	v_exp_f32_e32 v139, v139
	v_pk_add_f32 v[132:133], v[132:133], 1.0 op_sel_hi:[1,0]
	v_pk_add_f32 v[134:135], v[134:135], 1.0 op_sel_hi:[1,0]
	v_pk_add_f32 v[136:137], v[136:137], 1.0 op_sel_hi:[1,0]
	v_pk_add_f32 v[138:139], v[138:139], 1.0 op_sel_hi:[1,0]
	v_rcp_f32_e32 v132, v132
	v_rcp_f32_e32 v133, v133
	v_rcp_f32_e32 v134, v134
	v_rcp_f32_e32 v135, v135
	v_rcp_f32_e32 v136, v136
	v_rcp_f32_e32 v137, v137
	v_rcp_f32_e32 v138, v138
	v_rcp_f32_e32 v139, v139
	v_pk_mul_f32 v[132:133], v[42:43], v[132:133]
	v_pk_mul_f32 v[134:135], v[44:45], v[134:135]
	v_pk_mul_f32 v[136:137], v[34:35], v[136:137]
	v_pk_mul_f32 v[138:139], v[36:37], v[138:139]
	v_cvt_pk_bf16_f32 v144, v132, v133
	v_cvt_pk_bf16_f32 v145, v134, v135
	v_cvt_pk_bf16_f32 v146, v136, v137
	v_cvt_pk_bf16_f32 v147, v138, v139
	s_nop 1
	v_permlane16_swap_b32_e32 v144, v146
	v_permlane16_swap_b32_e32 v145, v147
	s_nop 1
	global_store_dwordx4 v173, v[144:147], s[4:5] offset:128 nt
	s_branch .LBB0_187
